# lever 7 continued: the lane^32 step of the mixer-B prologue reduction through v_permlane32_swap (one more LDS round trip removed per unit)
# speedup vs baseline: 1.0044x; 1.0024x over previous
; __device__ __forceinline__ unsigned cvtpk(float lo, float hi) { f32x2_t v = {lo, hi}; bf16x2_t b = __builtin_convertvector(v, bf16x2_t); return __builtin_bit_cast(unsigned, b); }
; __device__ __forceinline__ int tid_fresh() { int t = threadIdx.x; asm volatile("" : "+v"(t)); return t; }
; __device__ __forceinline__ float bflo(unsigned u) { return __uint_as_float(u << 16); }
; __device__ __forceinline__ float bfhi(unsigned u) { return __uint_as_float(u & 0xffff0000u); }
; #define WRITE_TILE(bufp) do { LAS unsigned char* _k = (bufp); LAS unsigned char* _v = (bufp) + 64 * KST; \
;         *(LAS u32x4*)(_k + key * KST + ch * 16) = kreg; \
;         *(LAS u32x4*)(_v + key * VST + ch * 16) = vreg; } while (0)
; __device__ __forceinline__ void attnB_unit(LAS unsigned char* lds, const Args& A, int unit, const float* kng, bool do_store = true) {
;     const int tid = tid_fresh(), wave = tid >> 6, lane = tid & 63, ql = lane & 31, hh = lane >> 5;
;     const int qblk = unit & 31, hq = (unit >> 5) & 7, b = unit >> 8, kvh = hq >> 2;
;     const bf16* Qp = (const bf16*)(A.ws + WS_QB) + ((size_t)((b * 8 + hq) * 8192 + qblk * 256 + wave * 32 + ql) * 64);
;     bf16x8 qf[4];
; #pragma unroll
;     for (int s = 0; s < 4; ++s) { const u32x4 qw = *(const u32x4*)(Qp + 16 * s + 8 * hh);
;         u32x4 qs; qs.x = cvtpk(bflo(qw.x) * QK_C, bfhi(qw.x) * QK_C); qs.y = cvtpk(bflo(qw.y) * QK_C, bfhi(qw.y) * QK_C); qs.z = cvtpk(bflo(qw.z) * QK_C, bfhi(qw.z) * QK_C); qs.w = cvtpk(bflo(qw.w) * QK_C, bfhi(qw.w) * QK_C);
;         qf[s] = __builtin_bit_cast(bf16x8, qs); }
;     const int key = tid >> 3, ch = tid & 7;
;     const bf16* Kg = (const bf16*)(A.ws + WS_KB) + ((size_t)((b * 2 + kvh) * 8192 + key) * 64 + ch * 8);
;     const bf16* Vg = (const bf16*)(A.ws + WS_VB) + ((size_t)((b * 2 + kvh) * 8192 + key) * 64 + ch * 8);
;     f32x16 o0, o1;
; #pragma unroll
;     for (int i = 0; i < 16; ++i) { o0[i] = 0.f; o1[i] = 0.f; }
;     float m_used = -1e30f, l = 0.f; float lp[4] = {0.f, 0.f, 0.f, 0.f};
;     u32x4 kreg = *(const u32x4*)Kg, vreg = *(const u32x4*)Vg;
;     u32x4 kq1 = *(const u32x4*)(Kg + (size_t)64 * 64), vq1 = *(const u32x4*)(Vg + (size_t)64 * 64), kq0 = *(const u32x4*)(Kg + (size_t)2 * 64 * 64), vq0 = *(const u32x4*)(Vg + (size_t)2 * 64 * 64);
;     ...
;     __syncthreads();
;     WRITE_TILE(lds);
;     kreg = kq1; vreg = vq1;
;     WRITE_TILE(lds + BUF_B);
;     __syncthreads();
.LBB0_314:
	s_bfe_u32 s8, s4, 0x30005
	s_ashr_i32 s9, s4, 8
	s_lshl_b32 s5, s9, 16
	s_lshl_b32 s6, s8, 13
	s_lshl_b32 s7, s4, 8
	v_mov_b32_e32 v32, v212
	s_and_b32 s10, s7, 0x1f00
	s_or_b32 s5, s5, s6
	s_or_b32 s5, s5, s10
	v_and_b32_e32 v210, 31, v32
	v_ashrrev_i32_e32 v0, 1, v32
	v_and_b32_e32 v211, 0xffffffe0, v0
	v_or_b32_e32 v0, s5, v210
	v_add_u32_e32 v0, v0, v211
	v_ashrrev_i32_e32 v1, 31, v0
	v_readlane_b32 s6, v254, 51
	v_bfe_u32 v33, v32, 5, 1
	v_lshlrev_b64 v[0:1], 7, v[0:1]
	v_readlane_b32 s7, v254, 52
	v_lshlrev_b32_e32 v184, 4, v33
	s_lshl_b32 s4, s4, 6
	v_lshl_add_u64 v[0:1], s[6:7], 0, v[0:1]
	v_lshl_add_u64 v[4:5], v[0:1], 0, v[184:185]
	global_load_dwordx4 v[20:23], v[4:5], off
	global_load_dwordx4 v[24:27], v[4:5], off offset:32
	global_load_dwordx4 v[28:31], v[4:5], off offset:64
	global_load_dwordx4 v[36:39], v[4:5], off offset:96
	s_lshl_b32 s5, s9, 14
	s_and_b32 s4, s4, 0x2000
	v_ashrrev_i32_e32 v34, 3, v32
	s_or_b32 s4, s4, s5
	v_mul_lo_u32 v224, v34, s88
	v_mul_u32_u24_e32 v225, 0x90, v210
	v_add3_u32 v44, 0, v225, v184
	v_and_b32_e32 v35, 63, v32
	v_lshlrev_b32_e32 v35, 2, v35
	v_mov_b32_e32 v172, 0
	v_readlane_b32 s6, v255, 48
	v_readlane_b32 s7, v255, 49
	v_lshlrev_b32_e32 v2, 4, v32
	v_and_b32_e32 v223, 0x70, v2
	v_add_u32_e32 v0, s4, v34
	v_ashrrev_i32_e32 v1, 31, v0
	v_lshlrev_b64 v[0:1], 7, v[0:1]
	v_readlane_b32 s4, v254, 53
	v_or_b32_e32 v0, v0, v223
	v_readlane_b32 s5, v254, 54
	global_load_dword v35, v35, s[6:7]
	s_nop 1
	v_lshl_add_u64 v[168:169], s[4:5], 0, v[0:1]
	v_readlane_b32 s4, v254, 8
	v_readlane_b32 s5, v254, 9
	s_nop 1
	v_lshl_add_u64 v[170:171], s[4:5], 0, v[0:1]
	s_movk_i32 s4, 0x2000
	v_add_co_u32_e32 v8, vcc, s4, v168
	global_load_dwordx4 v[0:3], v[168:169], off
	global_load_dwordx4 v[4:7], v[170:171], off
	v_addc_co_u32_e32 v9, vcc, 0, v169, vcc
	v_add_co_u32_e32 v12, vcc, s4, v170
	global_load_dwordx4 v[8:11], v[8:9], off
	s_nop 0
	v_addc_co_u32_e32 v13, vcc, 0, v171, vcc
	global_load_dwordx4 v[12:15], v[12:13], off
	s_movk_i32 s4, 0x4000
	v_add_co_u32_e32 v16, vcc, s4, v168
	s_nop 1
	v_addc_co_u32_e32 v17, vcc, 0, v169, vcc
	global_load_dwordx4 v[144:147], v[16:17], off
	v_add_co_u32_e32 v16, vcc, s4, v170
	s_movk_i32 s4, 0xffd0
	s_nop 0
	v_addc_co_u32_e32 v17, vcc, 0, v171, vcc
	global_load_dwordx4 v[148:151], v[16:17], off
	s_waitcnt vmcnt(6)
	v_lshlrev_b32_e32 v40, 16, v20
	v_and_b32_e32 v41, 0xffff0000, v20
	v_pk_mul_f32 v[40:41], v[40:41], s[92:93] op_sel_hi:[1,0]
	v_cvt_pk_bf16_f32 v128, v40, v41
	v_lshlrev_b32_e32 v42, 16, v21
	v_and_b32_e32 v43, 0xffff0000, v21
	v_pk_mul_f32 v[42:43], v[42:43], s[92:93] op_sel_hi:[1,0]
	v_cvt_pk_bf16_f32 v129, v42, v43
	v_lshlrev_b32_e32 v40, 16, v22
	v_and_b32_e32 v41, 0xffff0000, v22
	v_pk_mul_f32 v[40:41], v[40:41], s[92:93] op_sel_hi:[1,0]
	v_cvt_pk_bf16_f32 v130, v40, v41
	v_lshlrev_b32_e32 v42, 16, v23
	v_and_b32_e32 v43, 0xffff0000, v23
	v_pk_mul_f32 v[42:43], v[42:43], s[92:93] op_sel_hi:[1,0]
	v_cvt_pk_bf16_f32 v131, v42, v43
	v_lshlrev_b32_e32 v40, 16, v24
	v_and_b32_e32 v41, 0xffff0000, v24
	v_pk_mul_f32 v[40:41], v[40:41], s[92:93] op_sel_hi:[1,0]
	v_cvt_pk_bf16_f32 v132, v40, v41
	v_lshlrev_b32_e32 v42, 16, v25
	v_and_b32_e32 v43, 0xffff0000, v25
	v_pk_mul_f32 v[42:43], v[42:43], s[92:93] op_sel_hi:[1,0]
	v_cvt_pk_bf16_f32 v133, v42, v43
	v_lshlrev_b32_e32 v40, 16, v26
	v_and_b32_e32 v41, 0xffff0000, v26
	v_pk_mul_f32 v[40:41], v[40:41], s[92:93] op_sel_hi:[1,0]
	v_cvt_pk_bf16_f32 v134, v40, v41
	v_lshlrev_b32_e32 v42, 16, v27
	v_and_b32_e32 v43, 0xffff0000, v27
	v_pk_mul_f32 v[42:43], v[42:43], s[92:93] op_sel_hi:[1,0]
	v_cvt_pk_bf16_f32 v135, v42, v43
	v_lshlrev_b32_e32 v40, 16, v28
	v_and_b32_e32 v41, 0xffff0000, v28
	v_pk_mul_f32 v[40:41], v[40:41], s[92:93] op_sel_hi:[1,0]
	v_cvt_pk_bf16_f32 v136, v40, v41
	v_lshlrev_b32_e32 v42, 16, v29
	v_and_b32_e32 v43, 0xffff0000, v29
	v_pk_mul_f32 v[42:43], v[42:43], s[92:93] op_sel_hi:[1,0]
	v_cvt_pk_bf16_f32 v137, v42, v43
	v_lshlrev_b32_e32 v40, 16, v30
	v_and_b32_e32 v41, 0xffff0000, v30
	v_pk_mul_f32 v[40:41], v[40:41], s[92:93] op_sel_hi:[1,0]
	v_cvt_pk_bf16_f32 v138, v40, v41
	v_lshlrev_b32_e32 v42, 16, v31
	v_and_b32_e32 v43, 0xffff0000, v31
	v_pk_mul_f32 v[42:43], v[42:43], s[92:93] op_sel_hi:[1,0]
	v_cvt_pk_bf16_f32 v139, v42, v43
	v_lshlrev_b32_e32 v40, 16, v36
	v_and_b32_e32 v41, 0xffff0000, v36
	v_pk_mul_f32 v[40:41], v[40:41], s[92:93] op_sel_hi:[1,0]
	v_cvt_pk_bf16_f32 v140, v40, v41
	v_lshlrev_b32_e32 v42, 16, v37
	v_and_b32_e32 v43, 0xffff0000, v37
	v_pk_mul_f32 v[42:43], v[42:43], s[92:93] op_sel_hi:[1,0]
	v_cvt_pk_bf16_f32 v141, v42, v43
	v_lshlrev_b32_e32 v40, 16, v38
	v_and_b32_e32 v41, 0xffff0000, v38
	v_pk_mul_f32 v[40:41], v[40:41], s[92:93] op_sel_hi:[1,0]
	v_cvt_pk_bf16_f32 v142, v40, v41
	v_lshlrev_b32_e32 v42, 16, v39
	v_and_b32_e32 v43, 0xffff0000, v39
	v_pk_mul_f32 v[42:43], v[42:43], s[92:93] op_sel_hi:[1,0]
	v_cvt_pk_bf16_f32 v143, v42, v43
	v_and_b32_e32 v45, 0xffff0000, v140
	v_add3_u32 v16, 0, v224, v223
	s_barrier
	s_waitcnt vmcnt(5)
	ds_write_b128 v16, v[0:3]
	v_mul_lo_u32 v2, v34, 48
	v_add_u32_e32 v0, v16, v2
	s_waitcnt vmcnt(4)
	ds_write_b128 v0, v[4:7] offset:9216
	v_mad_u64_u32 v[0:1], s[4:5], v34, s4, v[0:1]
	s_waitcnt vmcnt(3)
	ds_write_b128 v0, v[8:11] offset:21504
	v_add_u32_e32 v0, v0, v2
	v_readlane_b32 s4, v255, 48
	s_waitcnt vmcnt(2)
	ds_write_b128 v0, v[12:15] offset:30720
	s_waitcnt lgkmcnt(0)
	s_barrier
; __device__ __forceinline__ float bflo(unsigned u) { return __uint_as_float(u << 16); }
; __device__ __forceinline__ float bfhi(unsigned u) { return __uint_as_float(u & 0xffff0000u); }
; #define QK_TILE(kbp, d0, d1) do { _Pragma("unroll") for (int s = 0; s < 4; ++s) { \
;         const bf16x8 _k0 = *(const LAS bf16x8*)((kbp) + ql * KST + hh * 16 + 32 * s), _k1 = *(const LAS bf16x8*)((kbp) + (32 + ql) * KST + hh * 16 + 32 * s); \
;         d0 = MFMA32(_k0, qf[s], d0); d1 = MFMA32(_k1, qf[s], d1); } } while (0)
; __device__ __forceinline__ void attnB_unit(LAS unsigned char* lds, const Args& A, int unit, const float* kng, bool do_store = true) {
;     ...
;     QK_TILE(lds, c0, c1);
;     float mx = fmaxf(c0[0], c1[0]);
; #pragma unroll
;     for (int i = 1; i < 16; ++i) mx = fmaxf(mx, fmaxf(c0[i], c1[i]));
;     mx = fmaxf(mx, __shfl_xor(mx, 32));
;     float qn2 = 0.f;
; #pragma unroll
;     for (int s = 0; s < 4; ++s) { const u32x4 qw = __builtin_bit_cast(u32x4, qf[s]);
;         qn2 += bflo(qw.x) * bflo(qw.x) + bfhi(qw.x) * bfhi(qw.x) + bflo(qw.y) * bflo(qw.y) + bfhi(qw.y) * bfhi(qw.y) + bflo(qw.z) * bflo(qw.z) + bfhi(qw.z) * bfhi(qw.z) + bflo(qw.w) * bflo(qw.w) + bfhi(qw.w) * bfhi(qw.w); }
;     qn2 += __shfl_xor(qn2, 32);
;     float gk = fabsf(kng[lane]);
; #pragma unroll
;     for (int o = 1; o < 64; o <<= 1) gk = fmaxf(gk, __shfl_xor(gk, o));
;     const bool fast = __all(sqrtf(qn2) * 8.0f * gk * 1.05f <= 48.0f) != 0;
	ds_read_b128 v[0:3], v44 offset:4608
	ds_read_b128 v[4:7], v44
	ds_read_b128 v[36:39], v44 offset:32
	ds_read_b128 v[40:43], v44 offset:4640
	s_waitcnt lgkmcnt(2)
	v_mfma_f32_32x32x16_bf16 v[16:31], v[4:7], v[128:131], 0
	v_readlane_b32 s5, v255, 49
	v_mfma_f32_32x32x16_bf16 v[0:15], v[0:3], v[128:131], 0
	s_waitcnt lgkmcnt(1)
	v_mfma_f32_32x32x16_bf16 v[16:31], v[36:39], v[132:135], v[16:31]
	s_waitcnt lgkmcnt(0)
	v_mfma_f32_32x32x16_bf16 v[0:15], v[40:43], v[132:135], v[0:15]
	ds_read_b128 v[36:39], v44 offset:64
	ds_read_b128 v[40:43], v44 offset:4672
	s_waitcnt lgkmcnt(1)
	v_mfma_f32_32x32x16_bf16 v[16:31], v[36:39], v[136:139], v[16:31]
	s_waitcnt lgkmcnt(0)
	v_mfma_f32_32x32x16_bf16 v[0:15], v[40:43], v[136:139], v[0:15]
	ds_read_b128 v[36:39], v44 offset:96
	ds_read_b128 v[40:43], v44 offset:4704
	v_and_b32_e32 v44, 0xffff0000, v136
	v_mul_f32_e64 v44, v44, v44
	v_mul_f32_e64 v45, v45, v45
	s_mov_b32 s4, 0xf800000
	s_waitcnt lgkmcnt(1)
	v_mfma_f32_32x32x16_bf16 v[16:31], v[36:39], v[140:143], v[16:31]
	s_waitcnt lgkmcnt(0)
	v_mfma_f32_32x32x16_bf16 v[0:15], v[40:43], v[140:143], v[0:15]
	s_nop 9
	v_max_f32_e32 v37, v17, v17
	v_max_f32_e32 v38, v18, v18
	v_max_f32_e32 v39, v19, v19
	v_and_b32_e32 v43, 0xffff0000, v132
	v_and_b32_e32 v42, 0xffff0000, v128
	v_lshlrev_b32_e32 v41, 16, v132
	v_lshlrev_b32_e32 v40, 16, v128
	v_max_f32_e32 v36, v1, v1
	v_max_f32_e32 v36, v37, v36
	v_max_f32_e32 v37, v2, v2
	v_max_f32_e32 v37, v38, v37
	v_max_f32_e32 v38, v3, v3
	v_max3_f32 v36, v16, v0, v36
	v_max_f32_e32 v38, v39, v38
	v_max3_f32 v36, v36, v37, v38
	v_max_f32_e32 v37, v4, v4
	v_max_f32_e32 v38, v20, v20
	v_max_f32_e32 v37, v38, v37
	v_max_f32_e32 v38, v5, v5
	v_max_f32_e32 v39, v21, v21
	v_max_f32_e32 v38, v39, v38
	v_max3_f32 v36, v36, v37, v38
	v_max_f32_e32 v37, v6, v6
	v_max_f32_e32 v38, v22, v22
	v_max_f32_e32 v37, v38, v37
	v_max_f32_e32 v38, v7, v7
	v_max_f32_e32 v39, v23, v23
	v_max_f32_e32 v38, v39, v38
	v_pk_mul_f32 v[42:43], v[42:43], v[42:43]
	v_max3_f32 v36, v36, v37, v38
	v_max_f32_e32 v37, v8, v8
	v_max_f32_e32 v38, v24, v24
	v_pk_fma_f32 v[40:41], v[40:41], v[40:41], v[42:43]
	v_lshlrev_b32_e32 v42, 16, v129
	v_lshlrev_b32_e32 v43, 16, v133
	v_max_f32_e32 v37, v38, v37
	v_max_f32_e32 v38, v9, v9
	v_max_f32_e32 v39, v25, v25
	v_pk_fma_f32 v[40:41], v[42:43], v[42:43], v[40:41]
	v_and_b32_e32 v43, 0xffff0000, v133
	v_and_b32_e32 v42, 0xffff0000, v129
	v_max_f32_e32 v38, v39, v38
	v_pk_fma_f32 v[40:41], v[42:43], v[42:43], v[40:41]
	v_lshlrev_b32_e32 v43, 16, v134
	v_lshlrev_b32_e32 v42, 16, v130
	v_max3_f32 v36, v36, v37, v38
	v_max_f32_e32 v37, v10, v10
	v_max_f32_e32 v38, v26, v26
	v_pk_fma_f32 v[40:41], v[42:43], v[42:43], v[40:41]
	v_and_b32_e32 v43, 0xffff0000, v134
	v_and_b32_e32 v42, 0xffff0000, v130
	v_max_f32_e32 v37, v38, v37
	v_max_f32_e32 v38, v11, v11
	v_max_f32_e32 v39, v27, v27
	v_pk_fma_f32 v[40:41], v[42:43], v[42:43], v[40:41]
	v_lshlrev_b32_e32 v43, 16, v135
	v_lshlrev_b32_e32 v42, 16, v131
	v_max_f32_e32 v38, v39, v38
	v_pk_fma_f32 v[40:41], v[42:43], v[42:43], v[40:41]
	v_and_b32_e32 v43, 0xffff0000, v135
	v_and_b32_e32 v42, 0xffff0000, v131
	v_max3_f32 v36, v36, v37, v38
	v_max_f32_e32 v37, v12, v12
	v_max_f32_e32 v38, v28, v28
	v_pk_fma_f32 v[40:41], v[42:43], v[42:43], v[40:41]
	v_lshlrev_b32_e32 v43, 16, v140
	v_lshlrev_b32_e32 v42, 16, v136
	v_max_f32_e32 v37, v38, v37
	v_max_f32_e32 v38, v13, v13
	v_max_f32_e32 v39, v29, v29
	v_pk_fma_f32 v[42:43], v[42:43], v[42:43], v[44:45]
	v_lshlrev_b32_e32 v44, 16, v137
	v_lshlrev_b32_e32 v45, 16, v141
	v_max_f32_e32 v38, v39, v38
	v_pk_fma_f32 v[42:43], v[44:45], v[44:45], v[42:43]
	v_and_b32_e32 v45, 0xffff0000, v141
	v_and_b32_e32 v44, 0xffff0000, v137
	v_max3_f32 v36, v36, v37, v38
	v_max_f32_e32 v37, v14, v14
	v_max_f32_e32 v38, v30, v30
	v_pk_fma_f32 v[42:43], v[44:45], v[44:45], v[42:43]
	v_lshlrev_b32_e32 v45, 16, v142
	v_lshlrev_b32_e32 v44, 16, v138
	v_max_f32_e32 v37, v38, v37
	v_max_f32_e32 v38, v15, v15
	v_max_f32_e32 v39, v31, v31
	v_pk_fma_f32 v[42:43], v[44:45], v[44:45], v[42:43]
	v_and_b32_e32 v45, 0xffff0000, v142
	v_and_b32_e32 v44, 0xffff0000, v138
	v_max_f32_e32 v38, v39, v38
	v_pk_fma_f32 v[42:43], v[44:45], v[44:45], v[42:43]
	v_lshlrev_b32_e32 v45, 16, v143
	v_lshlrev_b32_e32 v44, 16, v139
	v_max3_f32 v36, v36, v37, v38
	v_and_b32_e32 v38, 64, v217
	v_pk_fma_f32 v[42:43], v[44:45], v[44:45], v[42:43]
	v_and_b32_e32 v45, 0xffff0000, v143
	v_and_b32_e32 v44, 0xffff0000, v139
	v_xor_b32_e32 v37, 32, v217
	v_add_u32_e32 v38, 64, v38
	v_pk_fma_f32 v[42:43], v[44:45], v[44:45], v[42:43]
	v_add_f32_e32 v39, v40, v41
	v_cmp_lt_i32_e32 vcc, v37, v38
	v_add_f32_e32 v39, v39, v42
	v_xor_b32_e32 v42, 1, v217
	v_cndmask_b32_e32 v37, v217, v37, vcc
	v_cmp_lt_i32_e32 vcc, v42, v38
	s_waitcnt vmcnt(0)
	v_and_b32_e32 v41, 0x7fffffff, v35
	v_max_f32_e64 v35, |v35|, |v35|
	v_cndmask_b32_e32 v42, v217, v42, vcc
	v_lshlrev_b32_e32 v42, 2, v42
	v_lshlrev_b32_e32 v226, 2, v37
	v_add_f32_e32 v39, v39, v43
	ds_bpermute_b32 v40, v226, v39
	ds_bpermute_b32 v37, v226, v36
	s_nop 1
	v_max_f32_dpp v35, v35, v35 quad_perm:[1,0,3,2] row_mask:0xf bank_mask:0xf
	s_nop 1
	v_max_f32_dpp v35, v35, v35 quad_perm:[2,3,0,1] row_mask:0xf bank_mask:0xf
	s_nop 1
	v_max_f32_dpp v35, v35, v35 row_half_mirror row_mask:0xf bank_mask:0xf
	s_nop 1
	v_max_f32_dpp v35, v35, v35 row_mirror row_mask:0xf bank_mask:0xf
	s_nop 1
	v_xor_b32_e32 v41, 16, v217
	v_cmp_lt_i32_e32 vcc, v41, v38
	s_nop 1
	v_cndmask_b32_e32 v38, v217, v41, vcc
	v_lshlrev_b32_e32 v38, 2, v38
	ds_bpermute_b32 v38, v38, v35
	s_waitcnt lgkmcnt(0)
	v_max_f32_e32 v38, v38, v38
	v_max_f32_e32 v35, v35, v38
	v_mov_b32_e32 v38, v35
	v_mov_b32_e32 v41, v35
	s_nop 1
	v_permlane32_swap_b32_e32 v38, v41
	s_nop 0
	v_max_f32_e32 v35, v38, v41
	v_add_f32_e32 v38, v39, v40
	v_cmp_gt_f32_e32 vcc, s4, v38
	v_mul_f32_e32 v39, 0x4f800000, v38
	s_nop 0
	v_cndmask_b32_e32 v38, v38, v39, vcc
	v_sqrt_f32_e32 v39, v38
	s_nop 0
	v_add_u32_e32 v40, -1, v39
	v_fma_f32 v41, -v40, v39, v38
	v_cmp_ge_f32_e64 s[4:5], 0, v41
	v_add_u32_e32 v41, 1, v39
	s_nop 0
	v_cndmask_b32_e64 v40, v39, v40, s[4:5]
	v_fma_f32 v39, -v41, v39, v38
	v_cmp_lt_f32_e64 s[4:5], 0, v39
	s_nop 1
	v_cndmask_b32_e64 v39, v40, v41, s[4:5]
	v_mul_f32_e32 v40, 0x37800000, v39
	v_cndmask_b32_e32 v39, v39, v40, vcc
	v_cmp_class_f32_e32 vcc, v38, v216
	s_mov_b32 s4, 0x42400000
	s_nop 0
	v_cndmask_b32_e32 v38, v39, v38, vcc
	v_mul_f32_e32 v38, 0x41000000, v38
	v_mul_f32_e32 v35, v38, v35
	v_mul_f32_e32 v35, 0x3f866666, v35
	v_cmp_ge_f32_e32 vcc, s4, v35
	s_cmp_lg_u64 vcc, exec
	s_cselect_b64 s[4:5], -1, 0
	s_cmp_eq_u64 vcc, exec
	s_cbranch_scc1 .LBB0_316
; __device__ __forceinline__ void attnB_unit(LAS unsigned char* lds, const Args& A, int unit, const float* kng, bool do_store = true) {
;     ...
;     else {
;         m_used = mx;
; #pragma unroll
;         for (int i = 0; i < 16; ++i) { c0[i] -= m_used; c1[i] -= m_used; }
;         mx = 0.f;
	v_max_f32_e32 v35, v37, v37
	v_max_f32_e32 v36, v36, v36
	v_max_f32_e32 v172, v36, v35
	v_sub_f32_e32 v31, v31, v172
	v_sub_f32_e32 v30, v30, v172
	v_sub_f32_e32 v29, v29, v172
	v_sub_f32_e32 v28, v28, v172
	v_sub_f32_e32 v27, v27, v172
	v_sub_f32_e32 v26, v26, v172
	v_sub_f32_e32 v25, v25, v172
	v_sub_f32_e32 v24, v24, v172
	v_sub_f32_e32 v23, v23, v172
	v_sub_f32_e32 v22, v22, v172
	v_sub_f32_e32 v21, v21, v172
	v_sub_f32_e32 v20, v20, v172
	v_sub_f32_e32 v19, v19, v172
	v_sub_f32_e32 v18, v18, v172
	v_sub_f32_e32 v17, v17, v172
	v_sub_f32_e32 v16, v16, v172
	v_sub_f32_e32 v15, v15, v172
	v_sub_f32_e32 v14, v14, v172
	v_sub_f32_e32 v13, v13, v172
	v_sub_f32_e32 v12, v12, v172
	v_sub_f32_e32 v11, v11, v172
	v_sub_f32_e32 v10, v10, v172
	v_sub_f32_e32 v9, v9, v172
	v_sub_f32_e32 v8, v8, v172
	v_sub_f32_e32 v7, v7, v172
	v_sub_f32_e32 v6, v6, v172
	v_sub_f32_e32 v5, v5, v172
	v_sub_f32_e32 v4, v4, v172
	v_sub_f32_e32 v3, v3, v172
	v_sub_f32_e32 v2, v2, v172
	v_sub_f32_e32 v1, v1, v172
	v_sub_f32_e32 v0, v0, v172
